# MLA q rms chunk loads and rotary-key loop loads issued together (were one dependent round trip each)
# baseline (speedup 1.0000x reference)
; DI bf16_t f2bf(float x) { return (bf16_t)(pack2(x, 0.f) & 0xffffu); }
; DI float bflo(unsigned u) { return __uint_as_float(u << 16); }
; DI void mla_kv_tile(const Params& P, int pm, int pn, char* smem) {
;     ...
;     for (int i = 0; i < 16; ++i) { const int idx = tid + NT * i, row = idx >> 5, pi = idx & 31, m = m0 + row;
;       const float x1 = bflo((unsigned)proj[(size_t)m * DINP + C_BKR + pi]), x2 = bflo((unsigned)proj[(size_t)m * DINP + C_BKR + 32 + pi]);
;       double fr = (double)P.pos[m] * kInvFreq2Pi[pi]; fr -= floor(fr); const float ff = (float)fr;
;       const float sn = __builtin_amdgcn_sinf(ff), cs = __builtin_amdgcn_cosf(ff);
;       const bf16_t o1 = f2bf(x1 * cs - x2 * sn), o2 = f2bf(x2 * cs + x1 * sn);
; #pragma unroll
;       for (int hd = 0; hd < 4; ++hd) { bf16_t* kp = kmla + ((size_t)hd * S_ + m) * 192 + 128; kp[pi] = o1; kp[32 + pi] = o2; } }
.LBB0_411:
	v_and_b32_e32 v0, 31, v145
	v_lshlrev_b32_e32 v4, 3, v0
	s_getpc_b64 s[0:1]
	s_add_u32 s0, s0, kInvFreq2Pi@rel32@lo+4
	s_addc_u32 s1, s1, kInvFreq2Pi@rel32@hi+12
	global_load_dwordx2 v[2:3], v1, s[40:41] offset:1040
	v_lshlrev_b32_e32 v0, 1, v0
	global_load_dwordx2 v[4:5], v4, s[0:1]
	s_mov_b32 s0, 0
	s_waitcnt vmcnt(0)
.LBB0_412:
	v_add_u32_e32 v12, s0, v145
	v_ashrrev_i32_e32 v6, 5, v12
	v_add_u32_e32 v6, s5, v6
	v_mad_i64_i32 v[8:9], s[2:3], v6, s81, v[130:131]
	v_lshl_add_u64 v[8:9], v[8:9], 0, v[0:1]
	v_add_co_u32_e32 v8, vcc, 0x2000, v8
	v_ashrrev_i32_e32 v7, 31, v6
	s_nop 0
	v_addc_co_u32_e32 v9, vcc, 0, v9, vcc
	global_load_ushort v16, v[8:9], off offset:1184
	global_load_ushort v17, v[8:9], off offset:1248
	v_lshl_add_u64 v[8:9], v[6:7], 2, v[2:3]
	global_load_dword v18, v[8:9], off
	v_add_u32_e32 v20, 0x200, v12
	v_ashrrev_i32_e32 v20, 5, v20
	v_add_u32_e32 v20, s5, v20
	v_mad_i64_i32 v[8:9], s[2:3], v20, s81, v[130:131]
	v_lshl_add_u64 v[8:9], v[8:9], 0, v[0:1]
	v_add_co_u32_e32 v8, vcc, s83, v8
	v_ashrrev_i32_e32 v21, 31, v20
	s_nop 0
	v_addc_co_u32_e32 v9, vcc, 0, v9, vcc
	global_load_ushort v22, v[8:9], off offset:1184
	global_load_ushort v23, v[8:9], off offset:1248
	v_lshl_add_u64 v[8:9], v[20:21], 2, v[2:3]
	global_load_dword v24, v[8:9], off
	s_mov_b32 s1, 0xc00000
	s_waitcnt vmcnt(0)
	v_lshlrev_b32_e32 v13, 16, v16
	v_lshlrev_b32_e32 v14, 16, v17
	v_cvt_f64_i32_e32 v[8:9], v18
	v_mul_f64 v[10:11], v[4:5], v[8:9]
	v_floor_f64_e32 v[10:11], v[10:11]
	v_fma_f64 v[8:9], v[4:5], v[8:9], -v[10:11]
	v_cvt_f32_f64_e32 v7, v[8:9]
	v_sin_f32_e32 v8, v7
	v_cos_f32_e32 v7, v7
	v_mul_f32_e32 v9, v8, v14
	v_mul_f32_e32 v8, v8, v13
	v_fma_f32 v9, v7, v13, -v9
	v_fmac_f32_e32 v8, v7, v14
	v_mad_i64_i32 v[6:7], s[2:3], v6, s86, v[132:133]
	v_lshl_add_u64 v[6:7], v[6:7], 0, v[0:1]
	v_add_co_u32_e32 v10, vcc, s87, v6
	v_cvt_pk_bf16_f32 v15, v9, s0
	s_nop 0
	v_addc_co_u32_e32 v11, vcc, 0, v7, vcc
	v_cvt_pk_bf16_f32 v13, v8, s0
	global_store_short v[6:7], v15, off offset:256
	global_store_short v[6:7], v13, off offset:320
	v_lshl_add_u64 v[8:9], v[6:7], 0, s[52:53]
	global_store_short v[10:11], v15, off offset:256
	global_store_short v[8:9], v13, off offset:64
	v_add_co_u32_e32 v10, vcc, s1, v6
	v_lshl_add_u64 v[8:9], v[6:7], 0, s[50:51]
	s_nop 0
	v_addc_co_u32_e32 v11, vcc, 0, v7, vcc
	s_mov_b32 s1, 0x1200000
	global_store_short v[10:11], v15, off offset:256
	global_store_short v[8:9], v13, off offset:64
	v_lshl_add_u64 v[8:9], v[6:7], 0, s[36:37]
	v_add_co_u32_e32 v6, vcc, s1, v6
	s_nop 1
	v_addc_co_u32_e32 v7, vcc, 0, v7, vcc
	global_store_short v[6:7], v15, off offset:256
	global_store_short v[8:9], v13, off offset:64
	v_lshlrev_b32_e32 v12, 16, v22
	v_lshlrev_b32_e32 v13, 16, v23
	v_cvt_f64_i32_e32 v[8:9], v24
	v_mul_f64 v[10:11], v[4:5], v[8:9]
	v_floor_f64_e32 v[10:11], v[10:11]
	v_fma_f64 v[8:9], v[4:5], v[8:9], -v[10:11]
	v_cvt_f32_f64_e32 v7, v[8:9]
	v_sin_f32_e32 v8, v7
	v_cos_f32_e32 v7, v7
	v_mul_f32_e32 v9, v8, v13
	v_mul_f32_e32 v8, v8, v12
	v_fma_f32 v9, v7, v12, -v9
	v_fmac_f32_e32 v8, v7, v13
	v_mad_i64_i32 v[6:7], s[2:3], v20, s86, v[132:133]
	v_lshl_add_u64 v[6:7], v[6:7], 0, v[0:1]
	v_add_co_u32_e32 v10, vcc, s87, v6
	v_cvt_pk_bf16_f32 v14, v9, s0
	s_nop 0
	v_addc_co_u32_e32 v11, vcc, 0, v7, vcc
	v_cvt_pk_bf16_f32 v12, v8, s0
	global_store_short v[6:7], v14, off offset:256
	global_store_short v[6:7], v12, off offset:320
	v_lshl_add_u64 v[8:9], v[6:7], 0, s[52:53]
	global_store_short v[10:11], v14, off offset:256
	global_store_short v[8:9], v12, off offset:64
	v_add_co_u32_e32 v10, vcc, 0xc00000, v6
	v_lshl_add_u64 v[8:9], v[6:7], 0, s[50:51]
	s_nop 0
	v_addc_co_u32_e32 v11, vcc, 0, v7, vcc
	global_store_short v[10:11], v14, off offset:256
	global_store_short v[8:9], v12, off offset:64
	v_lshl_add_u64 v[8:9], v[6:7], 0, s[36:37]
	v_add_co_u32_e32 v6, vcc, 0x1200000, v6
	s_addk_i32 s0, 0x400
	s_nop 0
	v_addc_co_u32_e32 v7, vcc, 0, v7, vcc
	s_cmpk_lg_i32 s0, 0x2000
	global_store_short v[6:7], v14, off offset:256
	global_store_short v[8:9], v12, off offset:64
	s_cbranch_scc1 .LBB0_412

; DI void unpack8(const u32x4& v, float* f) { f[0] = bflo(v.x); f[1] = bfhi(v.x); f[2] = bflo(v.y); f[3] = bfhi(v.y); f[4] = bflo(v.z); f[5] = bfhi(v.z); f[6] = bflo(v.w); f[7] = bfhi(v.w); }
; DI void mla_q_tile(const Params& P, int pm, int pn, char* smem) {
;     ...
;   { const int row = tid >> 1, half = tid & 1; const bf16_t* p = proj + (size_t)(m0 + row) * DINP + C_BCQ + half * 224; float ss = 0.f;
;     for (int i = 0; i < 28; ++i) { const u32x4 v = *(const u32x4*)(p + i * 8); float f[8]; unpack8(v, f);
; #pragma unroll
;       for (int e = 0; e < 8; ++e) ss += f[e] * f[e]; }
;     ss += __shfl_xor(ss, 1); if (half == 0) rs[row] = rsqrtf(ss * (1.f / 448.f) + EPS); }
.LBB0_414:
	global_load_dwordx2 v[6:7], v1, s[40:41] offset:1224
	s_mul_hi_i32 s3, s4, 0x55555556
	s_lshr_b32 s0, s3, 31
	s_add_i32 s3, s3, s0
	v_mov_b32_e32 v0, v206
	s_lshl_b32 s2, s3, 8
	v_ashrrev_i32_e32 v8, 1, v0
	v_and_b32_e32 v9, 1, v0
	v_add_u32_e32 v0, s2, v8
	s_waitcnt vmcnt(0)
	v_mad_i64_i32 v[2:3], s[0:1], v0, s81, v[6:7]
	v_mul_u32_u24_e32 v0, 0xe0, v9
	v_lshlrev_b32_e32 v0, 1, v0
	v_lshl_add_u64 v[4:5], v[2:3], 0, v[0:1]
	s_mov_b64 s[0:1], 0x122ea020
	v_lshl_add_u64 v[2:3], v[4:5], 0, s[0:1]
	v_add_co_u32_e32 v4, vcc, s85, v4
	s_nop 1
	v_addc_co_u32_e32 v5, vcc, 0, v5, vcc
	global_load_dwordx4 v[10:13], v[4:5], off offset:32
	global_load_dwordx4 v[16:19], v[2:3], off offset:16
	global_load_dwordx4 v[20:23], v[2:3], off offset:32
	global_load_dwordx4 v[24:27], v[2:3], off offset:48
	global_load_dwordx4 v[28:31], v[2:3], off offset:64
	global_load_dwordx4 v[32:35], v[2:3], off offset:80
	global_load_dwordx4 v[36:39], v[2:3], off offset:96
	global_load_dwordx4 v[40:43], v[2:3], off offset:112
	global_load_dwordx4 v[44:47], v[2:3], off offset:128
	global_load_dwordx4 v[48:51], v[2:3], off offset:144
	global_load_dwordx4 v[52:55], v[2:3], off offset:160
	global_load_dwordx4 v[56:59], v[2:3], off offset:176
	global_load_dwordx4 v[60:63], v[2:3], off offset:192
	global_load_dwordx4 v[64:67], v[2:3], off offset:208
	global_load_dwordx4 v[68:71], v[2:3], off offset:224
	global_load_dwordx4 v[72:75], v[2:3], off offset:240
	global_load_dwordx4 v[76:79], v[2:3], off offset:256
	global_load_dwordx4 v[80:83], v[2:3], off offset:272
	global_load_dwordx4 v[84:87], v[2:3], off offset:288
	global_load_dwordx4 v[88:91], v[2:3], off offset:304
	global_load_dwordx4 v[92:95], v[2:3], off offset:320
	global_load_dwordx4 v[96:99], v[2:3], off offset:336
	global_load_dwordx4 v[100:103], v[2:3], off offset:352
	global_load_dwordx4 v[104:107], v[2:3], off offset:368
	global_load_dwordx4 v[108:111], v[2:3], off offset:384
	global_load_dwordx4 v[112:115], v[2:3], off offset:400
	s_waitcnt vmcnt(0) lgkmcnt(0)
	v_and_b32_e32 v0, 0xffff0000, v10
	v_lshlrev_b32_e32 v4, 16, v10
	v_mul_f32_e32 v0, v0, v0
	v_lshlrev_b32_e32 v5, 16, v11
	v_fmac_f32_e32 v0, v4, v4
	v_and_b32_e32 v10, 0xffff0000, v11
	v_fmac_f32_e32 v0, v5, v5
	v_lshlrev_b32_e32 v11, 16, v12
	v_fmac_f32_e32 v0, v10, v10
	v_and_b32_e32 v12, 0xffff0000, v12
	v_fmac_f32_e32 v0, v11, v11
	v_lshlrev_b32_e32 v14, 16, v13
	v_fmac_f32_e32 v0, v12, v12
	v_and_b32_e32 v13, 0xffff0000, v13
	v_fmac_f32_e32 v0, v14, v14
	v_fmac_f32_e32 v0, v13, v13
	v_lshlrev_b32_e32 v4, 16, v16
	v_and_b32_e32 v5, 0xffff0000, v16
	v_fmac_f32_e32 v0, v4, v4
	v_lshlrev_b32_e32 v16, 16, v17
	v_fmac_f32_e32 v0, v5, v5
	v_and_b32_e32 v17, 0xffff0000, v17
	v_fmac_f32_e32 v0, v16, v16
	v_lshlrev_b32_e32 v14, 16, v18
	v_fmac_f32_e32 v0, v17, v17
	v_and_b32_e32 v18, 0xffff0000, v18
	v_fmac_f32_e32 v0, v14, v14
	v_lshlrev_b32_e32 v15, 16, v19
	v_fmac_f32_e32 v0, v18, v18
	v_and_b32_e32 v19, 0xffff0000, v19
	v_fmac_f32_e32 v0, v15, v15
	v_fmac_f32_e32 v0, v19, v19
	v_lshlrev_b32_e32 v4, 16, v20
	v_and_b32_e32 v5, 0xffff0000, v20
	v_fmac_f32_e32 v0, v4, v4
	v_lshlrev_b32_e32 v20, 16, v21
	v_fmac_f32_e32 v0, v5, v5
	v_and_b32_e32 v21, 0xffff0000, v21
	v_fmac_f32_e32 v0, v20, v20
	v_lshlrev_b32_e32 v14, 16, v22
	v_fmac_f32_e32 v0, v21, v21
	v_and_b32_e32 v22, 0xffff0000, v22
	v_fmac_f32_e32 v0, v14, v14
	v_lshlrev_b32_e32 v15, 16, v23
	v_fmac_f32_e32 v0, v22, v22
	v_and_b32_e32 v23, 0xffff0000, v23
	v_fmac_f32_e32 v0, v15, v15
	v_fmac_f32_e32 v0, v23, v23
	v_lshlrev_b32_e32 v4, 16, v24
	v_and_b32_e32 v5, 0xffff0000, v24
	v_fmac_f32_e32 v0, v4, v4
	v_lshlrev_b32_e32 v24, 16, v25
	v_fmac_f32_e32 v0, v5, v5
	v_and_b32_e32 v25, 0xffff0000, v25
	v_fmac_f32_e32 v0, v24, v24
	v_lshlrev_b32_e32 v14, 16, v26
	v_fmac_f32_e32 v0, v25, v25
	v_and_b32_e32 v26, 0xffff0000, v26
	v_fmac_f32_e32 v0, v14, v14
	v_lshlrev_b32_e32 v15, 16, v27
	v_fmac_f32_e32 v0, v26, v26
	v_and_b32_e32 v27, 0xffff0000, v27
	v_fmac_f32_e32 v0, v15, v15
	v_fmac_f32_e32 v0, v27, v27
	v_lshlrev_b32_e32 v4, 16, v28
	v_and_b32_e32 v5, 0xffff0000, v28
	v_fmac_f32_e32 v0, v4, v4
	v_lshlrev_b32_e32 v28, 16, v29
	v_fmac_f32_e32 v0, v5, v5
	v_and_b32_e32 v29, 0xffff0000, v29
	v_fmac_f32_e32 v0, v28, v28
	v_lshlrev_b32_e32 v14, 16, v30
	v_fmac_f32_e32 v0, v29, v29
	v_and_b32_e32 v30, 0xffff0000, v30
	v_fmac_f32_e32 v0, v14, v14
	v_lshlrev_b32_e32 v15, 16, v31
	v_fmac_f32_e32 v0, v30, v30
	v_and_b32_e32 v31, 0xffff0000, v31
	v_fmac_f32_e32 v0, v15, v15
	v_fmac_f32_e32 v0, v31, v31
	v_lshlrev_b32_e32 v4, 16, v32
	v_and_b32_e32 v5, 0xffff0000, v32
	v_fmac_f32_e32 v0, v4, v4
	v_lshlrev_b32_e32 v32, 16, v33
	v_fmac_f32_e32 v0, v5, v5
	v_and_b32_e32 v33, 0xffff0000, v33
	v_fmac_f32_e32 v0, v32, v32
	v_lshlrev_b32_e32 v14, 16, v34
	v_fmac_f32_e32 v0, v33, v33
	v_and_b32_e32 v34, 0xffff0000, v34
	v_fmac_f32_e32 v0, v14, v14
	v_lshlrev_b32_e32 v15, 16, v35
	v_fmac_f32_e32 v0, v34, v34
	v_and_b32_e32 v35, 0xffff0000, v35
	v_fmac_f32_e32 v0, v15, v15
	v_fmac_f32_e32 v0, v35, v35
	v_lshlrev_b32_e32 v4, 16, v36
	v_and_b32_e32 v5, 0xffff0000, v36
	v_fmac_f32_e32 v0, v4, v4
	v_lshlrev_b32_e32 v36, 16, v37
	v_fmac_f32_e32 v0, v5, v5
	v_and_b32_e32 v37, 0xffff0000, v37
	v_fmac_f32_e32 v0, v36, v36
	v_lshlrev_b32_e32 v14, 16, v38
	v_fmac_f32_e32 v0, v37, v37
	v_and_b32_e32 v38, 0xffff0000, v38
	v_fmac_f32_e32 v0, v14, v14
	v_lshlrev_b32_e32 v15, 16, v39
	v_fmac_f32_e32 v0, v38, v38
	v_and_b32_e32 v39, 0xffff0000, v39
	v_fmac_f32_e32 v0, v15, v15
	v_fmac_f32_e32 v0, v39, v39
	v_lshlrev_b32_e32 v4, 16, v40
	v_and_b32_e32 v5, 0xffff0000, v40
	v_fmac_f32_e32 v0, v4, v4
	v_lshlrev_b32_e32 v40, 16, v41
; DI void unpack8(const u32x4& v, float* f) { f[0] = bflo(v.x); f[1] = bfhi(v.x); f[2] = bflo(v.y); f[3] = bfhi(v.y); f[4] = bflo(v.z); f[5] = bfhi(v.z); f[6] = bflo(v.w); f[7] = bfhi(v.w); }
; DI void mla_q_tile(const Params& P, int pm, int pn, char* smem) {
;     ...
;     for (int i = 0; i < 28; ++i) { const u32x4 v = *(const u32x4*)(p + i * 8); float f[8]; unpack8(v, f);
; #pragma unroll
;       for (int e = 0; e < 8; ++e) ss += f[e] * f[e]; }
	v_fmac_f32_e32 v0, v5, v5
	v_and_b32_e32 v41, 0xffff0000, v41
	v_fmac_f32_e32 v0, v40, v40
	v_lshlrev_b32_e32 v14, 16, v42
	v_fmac_f32_e32 v0, v41, v41
	v_and_b32_e32 v42, 0xffff0000, v42
	v_fmac_f32_e32 v0, v14, v14
	v_lshlrev_b32_e32 v15, 16, v43
	v_fmac_f32_e32 v0, v42, v42
	v_and_b32_e32 v43, 0xffff0000, v43
	v_fmac_f32_e32 v0, v15, v15
	v_fmac_f32_e32 v0, v43, v43
	v_lshlrev_b32_e32 v4, 16, v44
	v_and_b32_e32 v5, 0xffff0000, v44
	v_fmac_f32_e32 v0, v4, v4
	v_lshlrev_b32_e32 v44, 16, v45
	v_fmac_f32_e32 v0, v5, v5
	v_and_b32_e32 v45, 0xffff0000, v45
	v_fmac_f32_e32 v0, v44, v44
	v_lshlrev_b32_e32 v14, 16, v46
	v_fmac_f32_e32 v0, v45, v45
	v_and_b32_e32 v46, 0xffff0000, v46
	v_fmac_f32_e32 v0, v14, v14
	v_lshlrev_b32_e32 v15, 16, v47
	v_fmac_f32_e32 v0, v46, v46
	v_and_b32_e32 v47, 0xffff0000, v47
	v_fmac_f32_e32 v0, v15, v15
	v_fmac_f32_e32 v0, v47, v47
	v_lshlrev_b32_e32 v4, 16, v48
	v_and_b32_e32 v5, 0xffff0000, v48
	v_fmac_f32_e32 v0, v4, v4
	v_lshlrev_b32_e32 v48, 16, v49
	v_fmac_f32_e32 v0, v5, v5
	v_and_b32_e32 v49, 0xffff0000, v49
	v_fmac_f32_e32 v0, v48, v48
	v_lshlrev_b32_e32 v14, 16, v50
	v_fmac_f32_e32 v0, v49, v49
	v_and_b32_e32 v50, 0xffff0000, v50
	v_fmac_f32_e32 v0, v14, v14
	v_lshlrev_b32_e32 v15, 16, v51
	v_fmac_f32_e32 v0, v50, v50
	v_and_b32_e32 v51, 0xffff0000, v51
	v_fmac_f32_e32 v0, v15, v15
	v_fmac_f32_e32 v0, v51, v51
	v_lshlrev_b32_e32 v4, 16, v52
	v_and_b32_e32 v5, 0xffff0000, v52
	v_fmac_f32_e32 v0, v4, v4
	v_lshlrev_b32_e32 v52, 16, v53
	v_fmac_f32_e32 v0, v5, v5
	v_and_b32_e32 v53, 0xffff0000, v53
	v_fmac_f32_e32 v0, v52, v52
	v_lshlrev_b32_e32 v14, 16, v54
	v_fmac_f32_e32 v0, v53, v53
	v_and_b32_e32 v54, 0xffff0000, v54
	v_fmac_f32_e32 v0, v14, v14
	v_lshlrev_b32_e32 v15, 16, v55
	v_fmac_f32_e32 v0, v54, v54
	v_and_b32_e32 v55, 0xffff0000, v55
	v_fmac_f32_e32 v0, v15, v15
	v_fmac_f32_e32 v0, v55, v55
	v_lshlrev_b32_e32 v4, 16, v56
	v_and_b32_e32 v5, 0xffff0000, v56
	v_fmac_f32_e32 v0, v4, v4
	v_lshlrev_b32_e32 v56, 16, v57
	v_fmac_f32_e32 v0, v5, v5
	v_and_b32_e32 v57, 0xffff0000, v57
	v_fmac_f32_e32 v0, v56, v56
	v_lshlrev_b32_e32 v14, 16, v58
	v_fmac_f32_e32 v0, v57, v57
	v_and_b32_e32 v58, 0xffff0000, v58
	v_fmac_f32_e32 v0, v14, v14
	v_lshlrev_b32_e32 v15, 16, v59
	v_fmac_f32_e32 v0, v58, v58
	v_and_b32_e32 v59, 0xffff0000, v59
	v_fmac_f32_e32 v0, v15, v15
	v_fmac_f32_e32 v0, v59, v59
	v_lshlrev_b32_e32 v4, 16, v60
	v_and_b32_e32 v5, 0xffff0000, v60
	v_fmac_f32_e32 v0, v4, v4
	v_lshlrev_b32_e32 v60, 16, v61
	v_fmac_f32_e32 v0, v5, v5
	v_and_b32_e32 v61, 0xffff0000, v61
	v_fmac_f32_e32 v0, v60, v60
	v_lshlrev_b32_e32 v14, 16, v62
	v_fmac_f32_e32 v0, v61, v61
	v_and_b32_e32 v62, 0xffff0000, v62
	v_fmac_f32_e32 v0, v14, v14
	v_lshlrev_b32_e32 v15, 16, v63
	v_fmac_f32_e32 v0, v62, v62
	v_and_b32_e32 v63, 0xffff0000, v63
	v_fmac_f32_e32 v0, v15, v15
	v_fmac_f32_e32 v0, v63, v63
	v_lshlrev_b32_e32 v4, 16, v64
	v_and_b32_e32 v5, 0xffff0000, v64
	v_fmac_f32_e32 v0, v4, v4
	v_lshlrev_b32_e32 v64, 16, v65
	v_fmac_f32_e32 v0, v5, v5
	v_and_b32_e32 v65, 0xffff0000, v65
	v_fmac_f32_e32 v0, v64, v64
	v_lshlrev_b32_e32 v14, 16, v66
	v_fmac_f32_e32 v0, v65, v65
	v_and_b32_e32 v66, 0xffff0000, v66
	v_fmac_f32_e32 v0, v14, v14
	v_lshlrev_b32_e32 v15, 16, v67
	v_fmac_f32_e32 v0, v66, v66
	v_and_b32_e32 v67, 0xffff0000, v67
	v_fmac_f32_e32 v0, v15, v15
	v_fmac_f32_e32 v0, v67, v67
	v_lshlrev_b32_e32 v4, 16, v68
	v_and_b32_e32 v5, 0xffff0000, v68
	v_fmac_f32_e32 v0, v4, v4
	v_lshlrev_b32_e32 v68, 16, v69
	v_fmac_f32_e32 v0, v5, v5
	v_and_b32_e32 v69, 0xffff0000, v69
	v_fmac_f32_e32 v0, v68, v68
	v_lshlrev_b32_e32 v14, 16, v70
	v_fmac_f32_e32 v0, v69, v69
	v_and_b32_e32 v70, 0xffff0000, v70
	v_fmac_f32_e32 v0, v14, v14
	v_lshlrev_b32_e32 v15, 16, v71
	v_fmac_f32_e32 v0, v70, v70
	v_and_b32_e32 v71, 0xffff0000, v71
	v_fmac_f32_e32 v0, v15, v15
	v_fmac_f32_e32 v0, v71, v71
	v_lshlrev_b32_e32 v4, 16, v72
	v_and_b32_e32 v5, 0xffff0000, v72
	v_fmac_f32_e32 v0, v4, v4
	v_lshlrev_b32_e32 v72, 16, v73
	v_fmac_f32_e32 v0, v5, v5
	v_and_b32_e32 v73, 0xffff0000, v73
	v_fmac_f32_e32 v0, v72, v72
	v_lshlrev_b32_e32 v14, 16, v74
	v_fmac_f32_e32 v0, v73, v73
	v_and_b32_e32 v74, 0xffff0000, v74
	v_fmac_f32_e32 v0, v14, v14
	v_lshlrev_b32_e32 v15, 16, v75
	v_fmac_f32_e32 v0, v74, v74
	v_and_b32_e32 v75, 0xffff0000, v75
	v_fmac_f32_e32 v0, v15, v15
	v_fmac_f32_e32 v0, v75, v75
	v_lshlrev_b32_e32 v4, 16, v76
	v_and_b32_e32 v5, 0xffff0000, v76
	v_fmac_f32_e32 v0, v4, v4
	v_lshlrev_b32_e32 v76, 16, v77
	v_fmac_f32_e32 v0, v5, v5
	v_and_b32_e32 v77, 0xffff0000, v77
	v_fmac_f32_e32 v0, v76, v76
	v_lshlrev_b32_e32 v14, 16, v78
	v_fmac_f32_e32 v0, v77, v77
	v_and_b32_e32 v78, 0xffff0000, v78
	v_fmac_f32_e32 v0, v14, v14
	v_lshlrev_b32_e32 v15, 16, v79
	v_fmac_f32_e32 v0, v78, v78
	v_and_b32_e32 v79, 0xffff0000, v79
	v_fmac_f32_e32 v0, v15, v15
	v_fmac_f32_e32 v0, v79, v79
	v_lshlrev_b32_e32 v4, 16, v80
	v_and_b32_e32 v5, 0xffff0000, v80
	v_fmac_f32_e32 v0, v4, v4
	v_lshlrev_b32_e32 v80, 16, v81
	v_fmac_f32_e32 v0, v5, v5
	v_and_b32_e32 v81, 0xffff0000, v81
	v_fmac_f32_e32 v0, v80, v80
	v_lshlrev_b32_e32 v14, 16, v82
	v_fmac_f32_e32 v0, v81, v81
	v_and_b32_e32 v82, 0xffff0000, v82
	v_fmac_f32_e32 v0, v14, v14
	v_lshlrev_b32_e32 v15, 16, v83
	v_fmac_f32_e32 v0, v82, v82
	v_and_b32_e32 v83, 0xffff0000, v83
	v_fmac_f32_e32 v0, v15, v15
	v_fmac_f32_e32 v0, v83, v83
	v_lshlrev_b32_e32 v4, 16, v84
	v_and_b32_e32 v5, 0xffff0000, v84
	v_fmac_f32_e32 v0, v4, v4
	v_lshlrev_b32_e32 v84, 16, v85
	v_fmac_f32_e32 v0, v5, v5
	v_and_b32_e32 v85, 0xffff0000, v85
	v_fmac_f32_e32 v0, v84, v84
	v_lshlrev_b32_e32 v14, 16, v86
	v_fmac_f32_e32 v0, v85, v85
; DI void unpack8(const u32x4& v, float* f) { f[0] = bflo(v.x); f[1] = bfhi(v.x); f[2] = bflo(v.y); f[3] = bfhi(v.y); f[4] = bflo(v.z); f[5] = bfhi(v.z); f[6] = bflo(v.w); f[7] = bfhi(v.w); }
; DI void mla_q_tile(const Params& P, int pm, int pn, char* smem) {
;     ...
;     for (int i = 0; i < 28; ++i) { const u32x4 v = *(const u32x4*)(p + i * 8); float f[8]; unpack8(v, f);
; #pragma unroll
;       for (int e = 0; e < 8; ++e) ss += f[e] * f[e]; }
;     ss += __shfl_xor(ss, 1); if (half == 0) rs[row] = rsqrtf(ss * (1.f / 448.f) + EPS); }
	v_and_b32_e32 v86, 0xffff0000, v86
	v_fmac_f32_e32 v0, v14, v14
	v_lshlrev_b32_e32 v15, 16, v87
	v_fmac_f32_e32 v0, v86, v86
	v_and_b32_e32 v87, 0xffff0000, v87
	v_fmac_f32_e32 v0, v15, v15
	v_fmac_f32_e32 v0, v87, v87
	v_lshlrev_b32_e32 v4, 16, v88
	v_and_b32_e32 v5, 0xffff0000, v88
	v_fmac_f32_e32 v0, v4, v4
	v_lshlrev_b32_e32 v88, 16, v89
	v_fmac_f32_e32 v0, v5, v5
	v_and_b32_e32 v89, 0xffff0000, v89
	v_fmac_f32_e32 v0, v88, v88
	v_lshlrev_b32_e32 v14, 16, v90
	v_fmac_f32_e32 v0, v89, v89
	v_and_b32_e32 v90, 0xffff0000, v90
	v_fmac_f32_e32 v0, v14, v14
	v_lshlrev_b32_e32 v15, 16, v91
	v_fmac_f32_e32 v0, v90, v90
	v_and_b32_e32 v91, 0xffff0000, v91
	v_fmac_f32_e32 v0, v15, v15
	v_fmac_f32_e32 v0, v91, v91
	v_lshlrev_b32_e32 v4, 16, v92
	v_and_b32_e32 v5, 0xffff0000, v92
	v_fmac_f32_e32 v0, v4, v4
	v_lshlrev_b32_e32 v92, 16, v93
	v_fmac_f32_e32 v0, v5, v5
	v_and_b32_e32 v93, 0xffff0000, v93
	v_fmac_f32_e32 v0, v92, v92
	v_lshlrev_b32_e32 v14, 16, v94
	v_fmac_f32_e32 v0, v93, v93
	v_and_b32_e32 v94, 0xffff0000, v94
	v_fmac_f32_e32 v0, v14, v14
	v_lshlrev_b32_e32 v15, 16, v95
	v_fmac_f32_e32 v0, v94, v94
	v_and_b32_e32 v95, 0xffff0000, v95
	v_fmac_f32_e32 v0, v15, v15
	v_fmac_f32_e32 v0, v95, v95
	v_lshlrev_b32_e32 v4, 16, v96
	v_and_b32_e32 v5, 0xffff0000, v96
	v_fmac_f32_e32 v0, v4, v4
	v_lshlrev_b32_e32 v96, 16, v97
	v_fmac_f32_e32 v0, v5, v5
	v_and_b32_e32 v97, 0xffff0000, v97
	v_fmac_f32_e32 v0, v96, v96
	v_lshlrev_b32_e32 v14, 16, v98
	v_fmac_f32_e32 v0, v97, v97
	v_and_b32_e32 v98, 0xffff0000, v98
	v_fmac_f32_e32 v0, v14, v14
	v_lshlrev_b32_e32 v15, 16, v99
	v_fmac_f32_e32 v0, v98, v98
	v_and_b32_e32 v99, 0xffff0000, v99
	v_fmac_f32_e32 v0, v15, v15
	v_fmac_f32_e32 v0, v99, v99
	v_lshlrev_b32_e32 v4, 16, v100
	v_and_b32_e32 v5, 0xffff0000, v100
	v_fmac_f32_e32 v0, v4, v4
	v_lshlrev_b32_e32 v100, 16, v101
	v_fmac_f32_e32 v0, v5, v5
	v_and_b32_e32 v101, 0xffff0000, v101
	v_fmac_f32_e32 v0, v100, v100
	v_lshlrev_b32_e32 v14, 16, v102
	v_fmac_f32_e32 v0, v101, v101
	v_and_b32_e32 v102, 0xffff0000, v102
	v_fmac_f32_e32 v0, v14, v14
	v_lshlrev_b32_e32 v15, 16, v103
	v_fmac_f32_e32 v0, v102, v102
	v_and_b32_e32 v103, 0xffff0000, v103
	v_fmac_f32_e32 v0, v15, v15
	v_fmac_f32_e32 v0, v103, v103
	v_lshlrev_b32_e32 v4, 16, v104
	v_and_b32_e32 v5, 0xffff0000, v104
	v_fmac_f32_e32 v0, v4, v4
	v_lshlrev_b32_e32 v104, 16, v105
	v_fmac_f32_e32 v0, v5, v5
	v_and_b32_e32 v105, 0xffff0000, v105
	v_fmac_f32_e32 v0, v104, v104
	v_lshlrev_b32_e32 v14, 16, v106
	v_fmac_f32_e32 v0, v105, v105
	v_and_b32_e32 v106, 0xffff0000, v106
	v_fmac_f32_e32 v0, v14, v14
	v_lshlrev_b32_e32 v15, 16, v107
	v_fmac_f32_e32 v0, v106, v106
	v_and_b32_e32 v107, 0xffff0000, v107
	v_fmac_f32_e32 v0, v15, v15
	v_fmac_f32_e32 v0, v107, v107
	v_lshlrev_b32_e32 v4, 16, v108
	v_and_b32_e32 v5, 0xffff0000, v108
	v_fmac_f32_e32 v0, v4, v4
	v_lshlrev_b32_e32 v108, 16, v109
	v_fmac_f32_e32 v0, v5, v5
	v_and_b32_e32 v109, 0xffff0000, v109
	v_fmac_f32_e32 v0, v108, v108
	v_lshlrev_b32_e32 v14, 16, v110
	v_fmac_f32_e32 v0, v109, v109
	v_and_b32_e32 v110, 0xffff0000, v110
	v_fmac_f32_e32 v0, v14, v14
	v_lshlrev_b32_e32 v15, 16, v111
	v_fmac_f32_e32 v0, v110, v110
	v_and_b32_e32 v111, 0xffff0000, v111
	v_fmac_f32_e32 v0, v15, v15
	v_fmac_f32_e32 v0, v111, v111
	v_lshlrev_b32_e32 v4, 16, v112
	v_and_b32_e32 v5, 0xffff0000, v112
	v_fmac_f32_e32 v0, v4, v4
	v_lshlrev_b32_e32 v112, 16, v113
	v_fmac_f32_e32 v0, v5, v5
	v_and_b32_e32 v113, 0xffff0000, v113
	v_fmac_f32_e32 v0, v112, v112
	v_lshlrev_b32_e32 v14, 16, v114
	v_fmac_f32_e32 v0, v113, v113
	v_and_b32_e32 v114, 0xffff0000, v114
	v_fmac_f32_e32 v0, v14, v14
	v_lshlrev_b32_e32 v15, 16, v115
	v_fmac_f32_e32 v0, v114, v114
	v_and_b32_e32 v115, 0xffff0000, v115
	v_fmac_f32_e32 v0, v15, v15
	v_fmac_f32_e32 v0, v115, v115
	global_load_dwordx4 v[10:13], v[2:3], off offset:416
	s_waitcnt vmcnt(0) lgkmcnt(0)
	v_lshlrev_b32_e32 v4, 16, v10
	v_and_b32_e32 v5, 0xffff0000, v10
	v_fmac_f32_e32 v0, v4, v4
	v_fmac_f32_e32 v0, v5, v5
	global_load_dwordx4 v[2:5], v[2:3], off offset:432
	v_lshlrev_b32_e32 v10, 16, v11
	v_and_b32_e32 v11, 0xffff0000, v11
	v_fmac_f32_e32 v0, v10, v10
	v_lshlrev_b32_e32 v14, 16, v12
	v_fmac_f32_e32 v0, v11, v11
	v_and_b32_e32 v12, 0xffff0000, v12
	v_fmac_f32_e32 v0, v14, v14
	v_lshlrev_b32_e32 v15, 16, v13
	v_fmac_f32_e32 v0, v12, v12
	v_and_b32_e32 v13, 0xffff0000, v13
	v_fmac_f32_e32 v0, v15, v15
	v_fmac_f32_e32 v0, v13, v13
	s_waitcnt vmcnt(0) lgkmcnt(0)
	v_lshlrev_b32_e32 v10, 16, v2
	v_and_b32_e32 v2, 0xffff0000, v2
	v_fmac_f32_e32 v0, v10, v10
	v_lshlrev_b32_e32 v11, 16, v3
	v_fmac_f32_e32 v0, v2, v2
	v_and_b32_e32 v3, 0xffff0000, v3
	v_fmac_f32_e32 v0, v11, v11
	v_lshlrev_b32_e32 v12, 16, v4
	v_fmac_f32_e32 v0, v3, v3
	v_and_b32_e32 v4, 0xffff0000, v4
	v_fmac_f32_e32 v0, v12, v12
	v_mbcnt_hi_u32_b32 v2, -1, v207
	v_fmac_f32_e32 v0, v4, v4
	v_and_b32_e32 v4, 64, v2
	v_xor_b32_e32 v3, 1, v2
	v_add_u32_e32 v4, 64, v4
	v_lshlrev_b32_e32 v13, 16, v5
	v_cmp_lt_i32_e32 vcc, v3, v4
	v_and_b32_e32 v5, 0xffff0000, v5
	v_fmac_f32_e32 v0, v13, v13
	v_cndmask_b32_e32 v2, v2, v3, vcc
	v_fmac_f32_e32 v0, v5, v5
	v_lshlrev_b32_e32 v2, 2, v2
	ds_bpermute_b32 v2, v2, v0
	v_cmp_eq_u32_e32 vcc, 0, v9
	s_and_saveexec_b64 s[0:1], vcc
	s_cbranch_execz .LBB0_276
	s_waitcnt lgkmcnt(0)
	v_add_f32_e32 v0, v0, v2
	v_fmamk_f32 v0, v0, 0x3b124925, v245
	v_mul_f32_e32 v2, 0x4b800000, v0
	v_cmp_gt_f32_e32 vcc, s84, v0
	s_nop 1
	v_cndmask_b32_e32 v0, v0, v2, vcc
	v_rsq_f32_e32 v0, v0
	s_nop 0
	v_mul_f32_e32 v2, 0x45800000, v0
	v_cndmask_b32_e32 v0, v0, v2, vcc
	v_lshl_add_u32 v2, v8, 2, v240
	ds_write_b32 v2, v0
	s_branch .LBB0_276
